# m1pre: M1 part B gate stage of all of a block's items computed up front, one item per wave (was wave 0 per item with all waves waiting)
# baseline (speedup 1.0000x reference)
;   __host__ __device__ __forceinline__ float* G() const { return (float*)(wsl() + OFF_G); }
;   __host__ __device__ __forceinline__ float* mloc() const { return (float*)(wsl() + OFF_MLOC); }
;   __host__ __device__ __forceinline__ float* bend() const { return (float*)(wsl() + OFF_BEND); }
; __device__ __forceinline__ float logsigmoidf_(float x) { return fminf(x, 0.0f) - log1pf(__expf(-fabsf(x))); }
; __device__ __forceinline__ int obid() { int t = blockIdx.x; asm volatile("" : "+s"(t)); return t; }
; __device__ __forceinline__ int mchunk_tok(int dir, int j, int r) {
;   if (dir == 0) return j * 64 + r;
;   int c = (j < 4) ? (3 - j) : (135 - j);
;   return c * 64 + 63 - r;
; __device__ __forceinline__ void m1_phase(const Params& p, char* smem) {
;     ...
;   for (int it = obid(); it < NCHAIN * NCHUNK; it += gridDim.x) {
;     int ci = it / NCHUNK, j = it - ci * NCHUNK;
;     int dir = ci & 1, h = (ci >> 1) & 3, b = ci >> 3;
;     int rowbase = b * TPB;
;     if (w == 0) {
;       int row = rowbase + mchunk_tok(dir, j, lane);
;       float gi = p.G()[(size_t)row * 16 + (2 * dir) * 4 + h] + p.mlstm_gate_b[(2 * dir) * 4 + h];
;       float gf = p.G()[(size_t)row * 16 + (2 * dir + 1) * 4 + h] + p.mlstm_gate_b[(2 * dir + 1) * 4 + h];
;       float bsum = logsigmoidf_(gf);
; #pragma unroll
;       for (int o = 1; o < 64; o <<= 1) { float t = __shfl_up(bsum, o); if (lane >= o) bsum += t; }
;       float be = __shfl(bsum, 63);
;       float gg = be - bsum + gi;
;       float ml = wave_max(gg);
;       wv[lane] = __expf(gg - ml);
;       if (lane == 0) { p.mloc()[it] = ml; p.bend()[it] = be; }
.LBB0_765:
	s_or_b64 exec, exec, s[4:5]
	s_mov_b32 s56, s82
	s_cmpk_gt_i32 s56, 0x83f
	s_cbranch_scc1 .LBB0_779
	s_waitcnt lgkmcnt(0)
	v_and_b32_e32 v1, 15, v8
	v_and_b32_e32 v0, 48, v10
	v_lshl_or_b32 v2, v18, 4, v1
	v_add_u32_e32 v0, 0, v0
	s_movk_i32 s4, 0x90
	v_mad_u64_u32 v[12:13], s[2:3], v2, s4, v[0:1]
	v_mul_lo_u32 v2, v8, s4
	v_add_u32_e32 v13, 0, v2
	v_ashrrev_i32_e32 v2, 3, v8
	v_and_b32_e32 v14, -8, v2
	s_movk_i32 s4, 0x48
	v_mul_lo_u32 v3, v14, s4
	v_lshl_add_u32 v11, v10, 2, 0
	v_or_b32_e32 v3, v3, v10
	v_or_b32_e32 v2, 7, v2
	v_lshl_add_u32 v38, v3, 1, 0
	v_mad_u64_u32 v[2:3], s[2:3], v2, s4, v[10:11]
	v_lshl_add_u32 v39, v2, 1, 0
	v_add_u32_e32 v2, 0x200, v8
	v_ashrrev_i32_e32 v2, 3, v2
	v_and_b32_e32 v16, -8, v2
	v_mul_lo_u32 v3, v16, s4
	v_or_b32_e32 v3, v3, v10
	v_or_b32_e32 v2, 7, v2
	v_lshl_add_u32 v40, v3, 1, 0
	v_mad_u64_u32 v[2:3], s[2:3], v2, s4, v[10:11]
	s_load_dwordx2 s[2:3], s[0:1], 0xf0
	v_lshl_add_u32 v41, v2, 1, 0
	v_lshlrev_b32_e32 v2, 5, v10
	v_lshlrev_b32_e32 v3, 11, v18
	s_movk_i32 s4, 0x600
	s_waitcnt lgkmcnt(0)
	s_add_u32 s58, s2, 0x7290000
	s_addc_u32 s59, s3, 0
	v_ashrrev_i32_e32 v9, 31, v8
	v_and_or_b32 v2, v2, s4, v3
	s_add_u32 s8, s2, 0xcd50000
	v_mul_u32_u24_e32 v4, 0x90, v1
	v_ashrrev_i32_e32 v19, 31, v2
	v_or_b32_e32 v20, v1, v2
	s_addc_u32 s9, s3, 0
	v_lshl_add_u64 v[2:3], v[8:9], 2, s[2:3]
	s_mov_b64 s[2:3], 0x113b7000
	v_cmp_gt_u32_e64 s[40:41], 64, v8
	v_cmp_eq_u32_e64 s[42:43], 0, v10
	v_cmp_gt_i32_e64 s[44:45], s85, v8
	v_cmp_gt_u32_e64 s[46:47], 2, v10
	v_cmp_gt_u32_e64 s[48:49], 4, v10
	v_cmp_gt_u32_e64 s[50:51], 8, v10
	v_cmp_gt_u32_e64 s[52:53], 16, v10
	v_cmp_gt_u32_e64 s[54:55], 32, v10
	v_ashrrev_i32_e32 v15, 31, v14
	v_ashrrev_i32_e32 v17, 31, v16
	v_ashrrev_i32_e32 v21, 31, v20
	v_lshl_add_u64 v[22:23], v[2:3], 0, s[2:3]
	v_mov_b32_e32 v18, v20
	v_or_b32_e32 v24, 16, v20
	v_mov_b32_e32 v25, v19
	v_or_b32_e32 v26, 32, v20
	v_mov_b32_e32 v27, v19
	v_or_b32_e32 v28, 48, v20
	v_mov_b32_e32 v29, v19
	v_or_b32_e32 v30, 64, v20
	v_mov_b32_e32 v31, v19
	v_or_b32_e32 v32, 0x50, v20
	v_mov_b32_e32 v33, v19
	v_or_b32_e32 v34, 0x60, v20
	v_mov_b32_e32 v35, v19
	v_or_b32_e32 v36, 0x70, v20
	v_mov_b32_e32 v37, v19
	v_add_u32_e32 v9, v0, v4
	s_mov_b32 s61, 0
	v_readfirstlane_b32 s62, v8
	s_lshr_b32 s62, s62, 6
	s_mul_i32 s63, s62, s80
	s_add_i32 s63, s63, s56
	s_lshl_b32 s64, s62, 8
.Lm1pre_item:
	s_cmpk_gt_i32 s63, 0x83f
	s_cbranch_scc1 .Lm1pre_done
	s_mul_hi_i32 s2, s63, 0x3e0f83e1
	s_lshr_b32 s3, s2, 31
	s_ashr_i32 s2, s2, 5
	s_add_i32 s2, s2, s3
	s_mul_i32 s12, s2, 0xffffff7c
	s_lshr_b32 s11, s2, 3
	s_add_i32 s12, s12, s63
	s_and_b32 s13, s2, 1
	s_bfe_u32 s10, s2, 0x20001
	s_mulk_i32 s11, 0x2100
	s_mov_b64 s[4:5], exec
	s_cmp_lg_u32 s13, 0
	s_mov_b64 s[2:3], -1
	s_cbranch_scc0 .Lm1pre_771
	s_cmp_gt_i32 s12, 3
	s_cselect_b32 s2, 0x87, 3
	s_sub_i32 s2, s2, s12
	s_lshl_b32 s2, s2, 6
	v_bitop3_b32 v0, s2, 63, v10 bitop3:0x36
	s_mov_b64 s[2:3], 0
.Lm1pre_771:
	s_andn2_b64 vcc, exec, s[2:3]
	s_cbranch_vccnz .Lm1pre_773
	v_lshl_or_b32 v0, s12, 6, v10
.Lm1pre_773:
	s_load_dwordx2 s[6:7], s[0:1], 0xf0
	s_load_dwordx2 s[2:3], s[0:1], 0x90
	v_add_u32_e32 v0, s11, v0
	v_ashrrev_i32_e32 v1, 31, v0
	v_lshlrev_b64 v[0:1], 6, v[0:1]
	s_waitcnt lgkmcnt(0)
	v_lshl_add_u64 v[0:1], s[6:7], 0, v[0:1]
	s_lshl_b32 s30, s13, 5
	v_lshl_add_u64 v[0:1], v[0:1], 0, s[30:31]
	s_lshl_b32 s14, s10, 2
	s_mov_b32 s15, s31
	v_lshl_add_u64 v[2:3], v[0:1], 0, s[14:15]
	s_mov_b64 s[16:17], 0x11186000
	v_lshl_add_u64 v[0:1], v[2:3], 0, s[16:17]
	s_or_b32 s14, s30, s14
	v_mov_b32_e32 v4, s14
	global_load_dword v5, v[0:1], off offset:16
	global_load_dword v6, v4, s[2:3] offset:16
	s_nop 0
	global_load_dword v0, v4, s[2:3]
	s_mov_b32 s2, 0xbfb8aa3b
	v_add_co_u32_e32 v2, vcc, 0x11186000, v2
	s_waitcnt vmcnt(0)
	v_add_f32_e32 v4, v5, v6
	v_mul_f32_e64 v5, |v4|, s2
	v_exp_f32_e32 v6, v5
	v_addc_co_u32_e32 v3, vcc, 0, v3, vcc
	global_load_dword v1, v[2:3], off
	v_and_b32_e32 v2, 64, v231
	v_add_u32_e32 v3, -1, v231
	v_add_f32_e32 v42, 1.0, v6
	v_cmp_lt_i32_e32 vcc, v3, v2
	v_min_f32_e32 v7, 0, v4
	v_add_f32_e32 v43, -1.0, v42
	v_frexp_mant_f32_e32 v44, v42
	v_cvt_f64_f32_e32 v[4:5], v42
	s_mov_b32 s2, 0x3f2aaaab
	v_cndmask_b32_e32 v3, v3, v231, vcc
	v_sub_f32_e32 v45, v43, v42
	v_frexp_exp_i32_f64_e32 v4, v[4:5]
	v_cmp_gt_f32_e32 vcc, s2, v44
	v_sub_f32_e32 v43, v6, v43
	v_add_f32_e32 v5, 1.0, v45
	v_subbrev_co_u32_e32 v4, vcc, 0, v4, vcc
	v_add_f32_e32 v5, v43, v5
	v_sub_u32_e32 v43, 0, v4
	v_cvt_f32_i32_e32 v4, v4
	v_ldexp_f32 v42, v42, v43
	v_ldexp_f32 v5, v5, v43
	v_add_f32_e32 v43, -1.0, v42
	v_add_f32_e32 v44, 1.0, v42
	v_add_f32_e32 v45, 1.0, v43
	v_add_f32_e32 v46, -1.0, v44
	v_sub_f32_e32 v45, v42, v45
	v_sub_f32_e32 v42, v42, v46
	v_mul_f32_e32 v46, 0x3f317218, v4
	v_add_f32_e32 v45, v5, v45
	v_add_f32_e32 v5, v5, v42
	s_mov_b32 s2, 0x3f317218
	v_fma_f32 v42, v4, s2, -v46
	v_add_f32_e32 v47, v43, v45
	v_add_f32_e32 v48, v44, v5
	v_fmac_f32_e32 v42, 0xb102e308, v4
	v_sub_f32_e32 v4, v47, v43
	v_sub_f32_e32 v43, v48, v44
	v_rcp_f32_e32 v44, v48
	v_add_f32_e32 v49, v46, v42
	v_sub_f32_e32 v5, v5, v43
	v_sub_f32_e32 v43, v49, v46
	v_sub_f32_e32 v42, v42, v43
	v_mul_f32_e32 v43, v47, v44
	v_sub_f32_e32 v4, v45, v4
	v_mul_f32_e32 v45, v48, v43
	v_fma_f32 v46, v43, v48, -v45
	v_fmac_f32_e32 v46, v43, v5
	v_add_f32_e32 v50, v45, v46
	v_sub_f32_e32 v51, v47, v50
	v_sub_f32_e32 v45, v50, v45
	v_sub_f32_e32 v47, v47, v51
	v_sub_f32_e32 v45, v45, v46
	v_sub_f32_e32 v46, v47, v50
	v_add_f32_e32 v4, v4, v46
	v_add_f32_e32 v4, v45, v4
	v_add_f32_e32 v45, v51, v4
	v_mul_f32_e32 v46, v44, v45
	v_sub_f32_e32 v47, v51, v45
;   __host__ __device__ __forceinline__ float* G() const { return (float*)(wsl() + OFF_G); }
;   __host__ __device__ __forceinline__ float* mloc() const { return (float*)(wsl() + OFF_MLOC); }
;   __host__ __device__ __forceinline__ float* bend() const { return (float*)(wsl() + OFF_BEND); }
; __device__ __forceinline__ float logsigmoidf_(float x) { return fminf(x, 0.0f) - log1pf(__expf(-fabsf(x))); }
; __device__ __forceinline__ int obid() { int t = blockIdx.x; asm volatile("" : "+s"(t)); return t; }
; __device__ __forceinline__ void m1_phase(const Params& p, char* smem) {
;     ...
;   for (int it = obid(); it < NCHAIN * NCHUNK; it += gridDim.x) {
;     int ci = it / NCHUNK, j = it - ci * NCHUNK;
;     int dir = ci & 1, h = (ci >> 1) & 3, b = ci >> 3;
;     int rowbase = b * TPB;
;     if (w == 0) {
;       int row = rowbase + mchunk_tok(dir, j, lane);
;       float gi = p.G()[(size_t)row * 16 + (2 * dir) * 4 + h] + p.mlstm_gate_b[(2 * dir) * 4 + h];
;       float gf = p.G()[(size_t)row * 16 + (2 * dir + 1) * 4 + h] + p.mlstm_gate_b[(2 * dir + 1) * 4 + h];
;       float bsum = logsigmoidf_(gf);
; #pragma unroll
;       for (int o = 1; o < 64; o <<= 1) { float t = __shfl_up(bsum, o); if (lane >= o) bsum += t; }
;       float be = __shfl(bsum, 63);
;       float gg = be - bsum + gi;
;       float ml = wave_max(gg);
;       wv[lane] = __expf(gg - ml);
;       if (lane == 0) { p.mloc()[it] = ml; p.bend()[it] = be; }
;     }
;     __syncthreads();
	v_mul_f32_e32 v50, v48, v46
	v_add_f32_e32 v4, v4, v47
	v_add_f32_e32 v47, v43, v46
	v_fma_f32 v48, v46, v48, -v50
	v_sub_f32_e32 v43, v47, v43
	v_fmac_f32_e32 v48, v46, v5
	v_sub_f32_e32 v5, v46, v43
	v_add_f32_e32 v43, v50, v48
	v_sub_f32_e32 v46, v43, v50
	v_sub_f32_e32 v50, v45, v43
	v_sub_f32_e32 v45, v45, v50
	v_sub_f32_e32 v43, v45, v43
	v_sub_f32_e32 v46, v46, v48
	v_add_f32_e32 v4, v4, v43
	v_add_f32_e32 v4, v46, v4
	v_add_f32_e32 v4, v50, v4
	v_mul_f32_e32 v4, v44, v4
	v_add_f32_e32 v4, v5, v4
	v_add_f32_e32 v5, v47, v4
	v_mul_f32_e32 v43, v5, v5
	v_fmamk_f32 v46, v43, 0x3e9b6dac, v165
	v_sub_f32_e32 v44, v5, v47
	v_ldexp_f32 v45, v5, 1
	v_mul_f32_e32 v5, v5, v43
	v_fmaak_f32 v43, v43, v46, 0x3f2aaada
	v_mul_f32_e32 v5, v5, v43
	v_add_f32_e32 v43, v45, v5
	v_sub_f32_e32 v4, v4, v44
	v_sub_f32_e32 v44, v43, v45
	v_ldexp_f32 v4, v4, 1
	v_sub_f32_e32 v5, v5, v44
	v_add_f32_e32 v4, v4, v5
	v_add_f32_e32 v5, v43, v4
	v_sub_f32_e32 v43, v5, v43
	v_add_f32_e32 v44, v49, v5
	v_sub_f32_e32 v4, v4, v43
	v_sub_f32_e32 v43, v44, v49
	v_sub_f32_e32 v45, v44, v43
	v_sub_f32_e32 v5, v5, v43
	v_add_f32_e32 v43, v42, v4
	v_sub_f32_e32 v45, v49, v45
	v_sub_f32_e32 v46, v43, v42
	v_add_f32_e32 v5, v5, v45
	v_sub_f32_e32 v45, v43, v46
	v_sub_f32_e32 v4, v4, v46
	v_sub_f32_e32 v42, v42, v45
	v_add_f32_e32 v5, v43, v5
	v_add_f32_e32 v4, v4, v42
	v_add_f32_e32 v42, v44, v5
	v_sub_f32_e32 v43, v42, v44
	v_sub_f32_e32 v5, v5, v43
	v_add_f32_e32 v4, v4, v5
	s_mov_b32 s2, 0x7f800000
	v_add_f32_e32 v4, v42, v4
	v_cmp_neq_f32_e32 vcc, s2, v6
	s_mov_b32 s2, 0x33800000
	v_lshlrev_b32_e32 v3, 2, v3
	v_cndmask_b32_e32 v4, v225, v4, vcc
	v_cmp_ngt_f32_e32 vcc, -1.0, v6
	v_add_u32_e32 v5, -2, v231
	s_waitcnt vmcnt(0)
	v_add_f32_e32 v0, v1, v0
	v_cndmask_b32_e32 v4, v226, v4, vcc
	v_cmp_neq_f32_e32 vcc, -1.0, v6
	s_nop 1
	v_cndmask_b32_e32 v4, v227, v4, vcc
	v_cmp_lt_f32_e64 vcc, |v6|, s2
	s_nop 1
	v_cndmask_b32_e32 v4, v4, v6, vcc
	v_sub_f32_e32 v4, v7, v4
	ds_bpermute_b32 v3, v3, v4
	v_cmp_lt_i32_e32 vcc, v5, v2
	v_add_u32_e32 v7, 64, v2
	v_xor_b32_e32 v6, 32, v231
	v_cndmask_b32_e32 v5, v5, v231, vcc
	s_waitcnt lgkmcnt(0)
	v_add_f32_e32 v3, v4, v3
	v_lshlrev_b32_e32 v5, 2, v5
	v_cndmask_b32_e64 v3, v3, v4, s[42:43]
	ds_bpermute_b32 v4, v5, v3
	v_add_u32_e32 v5, -4, v231
	v_cmp_lt_i32_e32 vcc, v5, v2
	s_waitcnt lgkmcnt(0)
	v_add_f32_e32 v4, v3, v4
	v_cndmask_b32_e32 v5, v5, v231, vcc
	v_lshlrev_b32_e32 v5, 2, v5
	v_cndmask_b32_e64 v3, v4, v3, s[46:47]
	ds_bpermute_b32 v4, v5, v3
	v_add_u32_e32 v5, -8, v231
	v_cmp_lt_i32_e32 vcc, v5, v2
	s_waitcnt lgkmcnt(0)
	v_add_f32_e32 v4, v3, v4
	v_cndmask_b32_e32 v5, v5, v231, vcc
	v_lshlrev_b32_e32 v5, 2, v5
	v_cndmask_b32_e64 v3, v4, v3, s[48:49]
	ds_bpermute_b32 v4, v5, v3
	v_add_u32_e32 v5, -16, v231
	v_cmp_lt_i32_e32 vcc, v5, v2
	s_waitcnt lgkmcnt(0)
	v_add_f32_e32 v4, v3, v4
	v_cndmask_b32_e32 v5, v5, v231, vcc
	v_lshlrev_b32_e32 v5, 2, v5
	v_cndmask_b32_e64 v3, v4, v3, s[50:51]
	ds_bpermute_b32 v4, v5, v3
	v_subrev_u32_e32 v5, 32, v231
	v_cmp_lt_i32_e32 vcc, v5, v2
	s_waitcnt lgkmcnt(0)
	v_add_f32_e32 v4, v3, v4
	v_cndmask_b32_e32 v5, v5, v231, vcc
	v_lshlrev_b32_e32 v5, 2, v5
	v_cndmask_b32_e64 v3, v4, v3, s[52:53]
	ds_bpermute_b32 v4, v5, v3
	v_bfrev_b32_e32 v5, 0.5
	v_lshl_or_b32 v5, v231, 2, v5
	v_cmp_lt_i32_e32 vcc, v6, v7
	s_waitcnt lgkmcnt(0)
	v_add_f32_e32 v2, v3, v4
	v_cndmask_b32_e64 v3, v2, v3, s[54:55]
	ds_bpermute_b32 v2, v5, v3
	v_cndmask_b32_e32 v4, v231, v6, vcc
	v_lshlrev_b32_e32 v4, 2, v4
	s_waitcnt lgkmcnt(0)
	v_sub_f32_e32 v1, v2, v3
	v_add_f32_e32 v1, v0, v1
	ds_bpermute_b32 v0, v4, v1
	v_xor_b32_e32 v3, 16, v231
	v_cmp_lt_i32_e32 vcc, v3, v7
	v_xor_b32_e32 v4, 8, v231
	s_waitcnt lgkmcnt(0)
	v_max_f32_e32 v0, v0, v0
	v_cndmask_b32_e32 v3, v231, v3, vcc
	v_lshlrev_b32_e32 v3, 2, v3
	v_max_f32_e32 v0, v1, v0
	ds_bpermute_b32 v3, v3, v0
	v_cmp_lt_i32_e32 vcc, v4, v7
	s_waitcnt lgkmcnt(0)
	v_max_f32_e32 v3, v3, v3
	v_cndmask_b32_e32 v4, v231, v4, vcc
	v_lshlrev_b32_e32 v4, 2, v4
	v_max_f32_e32 v0, v0, v3
	ds_bpermute_b32 v3, v4, v0
	v_xor_b32_e32 v4, 4, v231
	v_cmp_lt_i32_e32 vcc, v4, v7
	s_waitcnt lgkmcnt(0)
	v_max_f32_e32 v3, v3, v3
	v_cndmask_b32_e32 v4, v231, v4, vcc
	v_lshlrev_b32_e32 v4, 2, v4
	v_max_f32_e32 v0, v0, v3
	ds_bpermute_b32 v3, v4, v0
	v_xor_b32_e32 v4, 2, v231
	v_cmp_lt_i32_e32 vcc, v4, v7
	s_waitcnt lgkmcnt(0)
	v_max_f32_e32 v3, v3, v3
	v_cndmask_b32_e32 v4, v231, v4, vcc
	v_lshlrev_b32_e32 v4, 2, v4
	v_max_f32_e32 v0, v0, v3
	ds_bpermute_b32 v3, v4, v0
	v_xor_b32_e32 v4, 1, v231
	v_cmp_lt_i32_e32 vcc, v4, v7
	s_waitcnt lgkmcnt(0)
	v_max_f32_e32 v3, v3, v3
	v_cndmask_b32_e32 v4, v231, v4, vcc
	v_max_f32_e32 v0, v0, v3
	v_lshlrev_b32_e32 v3, 2, v4
	ds_bpermute_b32 v3, v3, v0
	s_waitcnt lgkmcnt(0)
	v_max_f32_e32 v3, v3, v3
	v_max_f32_e32 v0, v0, v3
	v_sub_f32_e32 v1, v1, v0
	v_mul_f32_e32 v1, 0x3fb8aa3b, v1
	v_exp_f32_e32 v1, v1
	v_add_u32_e32 v75, s64, v11
	ds_write_b32 v75, v1 offset:36864
	s_and_b64 exec, exec, s[42:43]
	s_cbranch_execz .Lm1pre_775
	s_mov_b32 s66, s63
	s_ashr_i32 s67, s63, 31
	s_lshl_b64 s[2:3], s[66:67], 2
	s_add_u32 s2, s6, s2
	s_addc_u32 s3, s7, s3
	global_store_dword v217, v0, s[2:3]
	global_store_dword v218, v2, s[2:3] offset:256
.Lm1pre_775:
	s_mov_b64 exec, s[4:5]
	s_cmp_eq_u32 s62, 0
	s_cbranch_scc0 .Lm1pre_done
	s_cmp_eq_u32 s64, 0
	s_cbranch_scc0 .Lm1pre_done
	s_movk_i32 s64, 0x800
	s_lshl_b32 s65, s80, 3
	s_add_i32 s63, s63, s65
	s_branch .Lm1pre_item
.Lm1pre_done:
	s_branch .LBB0_768
.LBB0_767:
	s_or_b64 exec, exec, s[4:5]
	s_add_i32 s56, s56, s80
	s_addk_i32 s61, 0x100
	s_cmpk_gt_i32 s56, 0x83f
	s_barrier
	s_cbranch_scc1 .LBB0_779

;   __host__ __device__ __forceinline__ bf16_t* ACT() const { return (bf16_t*)(wsl() + OFF_ACT); }
; __device__ __forceinline__ float bf2f(bf16_t h) { return __uint_as_float(((uint32_t)h) << 16); }
; __device__ __forceinline__ void m1_phase(const Params& p, char* smem) {
;     ...
;     __syncthreads();
; #pragma unroll
;     for (int i = 0; i < 2; ++i) {
;       int idx = tid + i * NTHR;
;       int r = idx & 63, fc = (idx >> 6) * 8;
;       int row = rowbase + mchunk_tok(dir, j, r);
;       const bf16_t* src = p.ACT() + (size_t)row * PW;
;       uint4 kv = *(const uint4*)(src + 1184 + h * 128 + fc);
;       uint4 vv = *(const uint4*)(src + 1696 + h * 128 + fc);
;       float wr = wv[r];
;       const bf16_t* ke = (const bf16_t*)&kv; const bf16_t* ve = (const bf16_t*)&vv;
; #pragma unroll
;       for (int e = 0; e < 8; ++e) {
;         Kt[(fc + e) * 72 + r] = ke[e];
;         Vt[(fc + e) * 72 + r] = f2bf(bf2f(ve[e]) * wr);
;       }
;     }
;     __syncthreads();
.LBB0_775:
	s_cmp_eq_u32 s13, 0
	s_cselect_b64 vcc, -1, 0
	s_cmp_gt_i32 s12, 3
	s_cselect_b32 s2, 0x87, 3
	s_sub_i32 s2, s2, s12
	s_lshl_b32 s2, s2, 6
	v_bitop3_b32 v0, s2, 63, v10 bitop3:0x36
	v_lshl_or_b32 v1, s12, 6, v10
	v_cndmask_b32_e32 v0, v0, v1, vcc
	v_add_u32_e32 v2, s11, v0
	v_mov_b64_e32 v[0:1], s[58:59]
	v_mad_i64_i32 v[0:1], s[2:3], v2, s84, v[0:1]
	s_lshl_b32 s30, s10, 8
	v_lshl_add_u64 v[44:45], v[0:1], 0, s[30:31]
	v_lshl_add_u64 v[4:5], v[14:15], 1, v[44:45]
	s_waitcnt vmcnt(0) lgkmcnt(0)
	s_barrier
	v_add_u32_e32 v74, s61, v11
	ds_read_b32 v42, v74 offset:36864
	global_load_dwordx4 v[0:3], v[4:5], off offset:2368
	s_nop 0
	global_load_dwordx4 v[4:7], v[4:5], off offset:3392
	s_ashr_i32 s57, s56, 31
	s_lshl_b64 s[2:3], s[56:57], 15
	s_add_u32 s4, s8, s2
	s_addc_u32 s5, s9, s3
	s_waitcnt vmcnt(1)
	ds_write_b16 v38, v0
	s_waitcnt vmcnt(0)
	v_lshlrev_b32_e32 v43, 16, v4
	s_waitcnt lgkmcnt(1)
	v_mul_f32_e32 v43, v42, v43
	v_bfe_u32 v46, v43, 16, 1
	v_add3_u32 v43, v43, v46, s28
	ds_write_b16_d16_hi v38, v43 offset:18432
	ds_write_b16_d16_hi v38, v0 offset:144
	v_and_b32_e32 v0, 0xffff0000, v4
	v_mul_f32_e32 v0, v42, v0
	v_bfe_u32 v4, v0, 16, 1
	v_add3_u32 v0, v0, v4, s28
	ds_write_b16_d16_hi v38, v0 offset:18576
	ds_write_b16 v38, v1 offset:288
	v_lshlrev_b32_e32 v0, 16, v5
	v_mul_f32_e32 v0, v42, v0
	v_bfe_u32 v4, v0, 16, 1
	v_add3_u32 v0, v0, v4, s28
	ds_write_b16_d16_hi v38, v0 offset:18720
	ds_write_b16_d16_hi v38, v1 offset:432
	v_and_b32_e32 v0, 0xffff0000, v5
	v_mul_f32_e32 v0, v42, v0
	v_bfe_u32 v1, v0, 16, 1
	v_add3_u32 v0, v0, v1, s28
	ds_write_b16_d16_hi v38, v0 offset:18864
	ds_write_b16 v38, v2 offset:576
	v_lshlrev_b32_e32 v0, 16, v6
	v_mul_f32_e32 v0, v42, v0
	v_bfe_u32 v1, v0, 16, 1
	v_add3_u32 v0, v0, v1, s28
	ds_write_b16_d16_hi v38, v0 offset:19008
	ds_write_b16_d16_hi v38, v2 offset:720
	v_and_b32_e32 v0, 0xffff0000, v6
	v_mul_f32_e32 v0, v42, v0
	v_bfe_u32 v1, v0, 16, 1
	v_add3_u32 v0, v0, v1, s28
	ds_write_b16_d16_hi v38, v0 offset:19152
	ds_write_b16 v38, v3 offset:864
	v_lshlrev_b32_e32 v0, 16, v7
	v_mul_f32_e32 v0, v42, v0
	v_bfe_u32 v1, v0, 16, 1
	v_add3_u32 v0, v0, v1, s28
	ds_write_b16_d16_hi v38, v0 offset:19296
	ds_write_b16_d16_hi v39, v3
	v_and_b32_e32 v0, 0xffff0000, v7
	v_mul_f32_e32 v0, v42, v0
	v_bfe_u32 v1, v0, 16, 1
	v_add3_u32 v0, v0, v1, s28
	ds_write_b16_d16_hi v39, v0 offset:18432
	v_lshl_add_u64 v[4:5], v[16:17], 1, v[44:45]
	global_load_dwordx4 v[0:3], v[4:5], off offset:2368
	s_nop 0
	global_load_dwordx4 v[4:7], v[4:5], off offset:3392
	s_waitcnt vmcnt(1)
	ds_write_b16 v40, v0
	s_waitcnt vmcnt(0)
	v_lshlrev_b32_e32 v43, 16, v4
	v_mul_f32_e32 v43, v42, v43
	v_bfe_u32 v44, v43, 16, 1
	v_add3_u32 v43, v43, v44, s28
	ds_write_b16_d16_hi v40, v43 offset:18432
	ds_write_b16_d16_hi v40, v0 offset:144
	v_and_b32_e32 v0, 0xffff0000, v4
	v_mul_f32_e32 v0, v42, v0
	v_bfe_u32 v4, v0, 16, 1
	v_add3_u32 v0, v0, v4, s28
	ds_write_b16_d16_hi v40, v0 offset:18576
	ds_write_b16 v40, v1 offset:288
	v_lshlrev_b32_e32 v0, 16, v5
	v_mul_f32_e32 v0, v42, v0
	v_bfe_u32 v4, v0, 16, 1
	v_add3_u32 v0, v0, v4, s28
	ds_write_b16_d16_hi v40, v0 offset:18720
	ds_write_b16_d16_hi v40, v1 offset:432
	v_and_b32_e32 v0, 0xffff0000, v5
	v_mul_f32_e32 v0, v42, v0
	v_bfe_u32 v1, v0, 16, 1
	v_add3_u32 v0, v0, v1, s28
	ds_write_b16_d16_hi v40, v0 offset:18864
	ds_write_b16 v40, v2 offset:576
	v_lshlrev_b32_e32 v0, 16, v6
	v_mul_f32_e32 v0, v42, v0
	v_bfe_u32 v1, v0, 16, 1
	v_add3_u32 v0, v0, v1, s28
	ds_write_b16_d16_hi v40, v0 offset:19008
	ds_write_b16_d16_hi v40, v2 offset:720
	v_and_b32_e32 v0, 0xffff0000, v6
	v_mul_f32_e32 v0, v42, v0
	v_bfe_u32 v1, v0, 16, 1
	v_add3_u32 v0, v0, v1, s28
	ds_write_b16_d16_hi v40, v0 offset:19152
	ds_write_b16 v40, v3 offset:864
	v_lshlrev_b32_e32 v0, 16, v7
	v_mul_f32_e32 v0, v42, v0
	v_bfe_u32 v1, v0, 16, 1
	v_add3_u32 v0, v0, v1, s28
	ds_write_b16_d16_hi v40, v0 offset:19296
	ds_write_b16_d16_hi v41, v3
	v_and_b32_e32 v0, 0xffff0000, v7
	v_mul_f32_e32 v0, v42, v0
	v_bfe_u32 v1, v0, 16, 1
	v_add3_u32 v0, v0, v1, s28
	ds_write_b16_d16_hi v41, v0 offset:18432
	s_waitcnt lgkmcnt(0)
	s_barrier
;   __host__ __device__ __forceinline__ float* dn() const { return (float*)(wsl() + OFF_DN); }
;   __host__ __device__ __forceinline__ bf16_t* R() const { return (bf16_t*)(wsl() + OFF_R); }
; __device__ __forceinline__ float bf2f(bf16_t h) { return __uint_as_float(((uint32_t)h) << 16); }
; #define MFMA16(a, b, c) __builtin_amdgcn_mfma_f32_16x16x32_bf16(a, b, c, 0, 0, 0)
; __device__ __forceinline__ void m1_phase(const Params& p, char* smem) {
;     ...
;     f32x4 acc[8];
; #pragma unroll
;     for (int ni = 0; ni < 8; ++ni) acc[ni] = (f32x4){0.f, 0.f, 0.f, 0.f};
; #pragma unroll
;     for (int ks = 0; ks < 2; ++ks) {
;       bf16x8 a = *(const bf16x8*)(Vt + (w * 16 + fr) * 72 + ks * 32 + fq * 8);
; #pragma unroll
;       for (int ni = 0; ni < 8; ++ni) {
;         bf16x8 bb = *(const bf16x8*)(Kt + (ni * 16 + fr) * 72 + ks * 32 + fq * 8);
;         acc[ni] = MFMA16(a, bb, acc[ni]);
;       }
;     }
;     bf16_t* dC = p.R() + (size_t)it * 16384;
; #pragma unroll
;     for (int ni = 0; ni < 8; ++ni)
; #pragma unroll
;       for (int jj = 0; jj < 4; ++jj) dC[(w * 16 + fq * 4 + jj) * 128 + ni * 16 + fr] = f2bf(acc[ni][jj]);
;     if (tid < 128) {
;       float s = 0;
; #pragma unroll 8
;       for (int r = 0; r < 64; ++r) s += wv[r] * bf2f(Kt[tid * 72 + r]);
;       p.dn()[(size_t)it * 128 + tid] = s;
;     }
;     __syncthreads();
	ds_read_b128 v[0:3], v12 offset:18432
	ds_read_b128 v[4:7], v9
	ds_read_b128 v[42:45], v9 offset:2304
	ds_read_b128 v[46:49], v9 offset:4608
	ds_read_b128 v[50:53], v9 offset:6912
	ds_read_b128 v[54:57], v9 offset:9216
	ds_read_b128 v[58:61], v9 offset:11520
	ds_read_b128 v[62:65], v9 offset:13824
	ds_read_b128 v[66:69], v9 offset:16128
	s_waitcnt lgkmcnt(7)
	v_mfma_f32_16x16x32_bf16 v[4:7], v[0:3], v[4:7], 0
	s_waitcnt lgkmcnt(6)
	v_mfma_f32_16x16x32_bf16 v[42:45], v[0:3], v[42:45], 0
	s_waitcnt lgkmcnt(5)
	v_mfma_f32_16x16x32_bf16 v[46:49], v[0:3], v[46:49], 0
	s_waitcnt lgkmcnt(4)
	v_mfma_f32_16x16x32_bf16 v[50:53], v[0:3], v[50:53], 0
	s_waitcnt lgkmcnt(3)
	v_mfma_f32_16x16x32_bf16 v[54:57], v[0:3], v[54:57], 0
	s_waitcnt lgkmcnt(2)
	v_mfma_f32_16x16x32_bf16 v[58:61], v[0:3], v[58:61], 0
	s_waitcnt lgkmcnt(1)
	v_mfma_f32_16x16x32_bf16 v[62:65], v[0:3], v[62:65], 0
	s_waitcnt lgkmcnt(0)
	v_mfma_f32_16x16x32_bf16 v[0:3], v[0:3], v[66:69], 0
	ds_read_b128 v[66:69], v12 offset:18496
	ds_read_b128 v[70:73], v9 offset:64
	s_waitcnt lgkmcnt(0)
	v_mfma_f32_16x16x32_bf16 v[4:7], v[66:69], v[70:73], v[4:7]
	ds_read_b128 v[70:73], v9 offset:2368
	s_waitcnt lgkmcnt(0)
	v_mfma_f32_16x16x32_bf16 v[42:45], v[66:69], v[70:73], v[42:45]
	ds_read_b128 v[70:73], v9 offset:4672
	s_waitcnt lgkmcnt(0)
	v_mfma_f32_16x16x32_bf16 v[46:49], v[66:69], v[70:73], v[46:49]
	ds_read_b128 v[70:73], v9 offset:6976
	s_waitcnt lgkmcnt(0)
	v_mfma_f32_16x16x32_bf16 v[50:53], v[66:69], v[70:73], v[50:53]
	ds_read_b128 v[70:73], v9 offset:9280
	s_waitcnt lgkmcnt(0)
	v_mfma_f32_16x16x32_bf16 v[54:57], v[66:69], v[70:73], v[54:57]
	ds_read_b128 v[70:73], v9 offset:11584
	s_waitcnt lgkmcnt(0)
	v_mfma_f32_16x16x32_bf16 v[58:61], v[66:69], v[70:73], v[58:61]
	ds_read_b128 v[70:73], v9 offset:13888
	s_waitcnt lgkmcnt(0)
	v_mfma_f32_16x16x32_bf16 v[62:65], v[66:69], v[70:73], v[62:65]
	ds_read_b128 v[70:73], v9 offset:16192
	s_waitcnt lgkmcnt(0)
	v_mfma_f32_16x16x32_bf16 v[0:3], v[66:69], v[70:73], v[0:3]
	v_bfe_u32 v66, v4, 16, 1
	v_add3_u32 v4, v4, v66, s28
	v_lshl_add_u64 v[66:67], v[20:21], 1, s[4:5]
	global_store_short_d16_hi v[66:67], v4, off
	v_bfe_u32 v4, v5, 16, 1
	v_add3_u32 v66, v5, v4, s28
	v_lshl_add_u64 v[4:5], v[18:19], 1, s[4:5]
	global_store_short_d16_hi v[4:5], v66, off offset:256
	v_bfe_u32 v66, v6, 16, 1
	v_add3_u32 v6, v6, v66, s28
	global_store_short_d16_hi v[4:5], v6, off offset:512
	v_bfe_u32 v6, v7, 16, 1
	v_add3_u32 v6, v7, v6, s28
	global_store_short_d16_hi v[4:5], v6, off offset:768
	v_bfe_u32 v6, v42, 16, 1
	v_add3_u32 v6, v42, v6, s28
	global_store_short_d16_hi v[4:5], v6, off offset:32
	v_bfe_u32 v6, v43, 16, 1
	v_add3_u32 v42, v43, v6, s28
	v_lshl_add_u64 v[6:7], v[24:25], 1, s[4:5]
	global_store_short_d16_hi v[6:7], v42, off offset:256
	v_bfe_u32 v42, v44, 16, 1
	v_add3_u32 v42, v44, v42, s28
	global_store_short_d16_hi v[6:7], v42, off offset:512
	v_bfe_u32 v42, v45, 16, 1
	v_add3_u32 v42, v45, v42, s28
	global_store_short_d16_hi v[6:7], v42, off offset:768
	v_bfe_u32 v6, v46, 16, 1
	v_add3_u32 v6, v46, v6, s28
	global_store_short_d16_hi v[4:5], v6, off offset:64
	v_bfe_u32 v6, v47, 16, 1
	v_add3_u32 v42, v47, v6, s28
	v_lshl_add_u64 v[6:7], v[26:27], 1, s[4:5]
	global_store_short_d16_hi v[6:7], v42, off offset:256
	v_bfe_u32 v42, v48, 16, 1
	v_add3_u32 v42, v48, v42, s28
	global_store_short_d16_hi v[6:7], v42, off offset:512
	v_bfe_u32 v42, v49, 16, 1
	v_add3_u32 v42, v49, v42, s28
	global_store_short_d16_hi v[6:7], v42, off offset:768
	v_bfe_u32 v6, v50, 16, 1
	v_add3_u32 v6, v50, v6, s28
	global_store_short_d16_hi v[4:5], v6, off offset:96
	v_bfe_u32 v6, v51, 16, 1
	v_add3_u32 v42, v51, v6, s28
	v_lshl_add_u64 v[6:7], v[28:29], 1, s[4:5]
	global_store_short_d16_hi v[6:7], v42, off offset:256
	v_bfe_u32 v42, v52, 16, 1
	v_add3_u32 v42, v52, v42, s28
	global_store_short_d16_hi v[6:7], v42, off offset:512
	v_bfe_u32 v42, v53, 16, 1
	v_add3_u32 v42, v53, v42, s28
	global_store_short_d16_hi v[6:7], v42, off offset:768
	v_bfe_u32 v6, v54, 16, 1
	v_add3_u32 v6, v54, v6, s28
	global_store_short_d16_hi v[4:5], v6, off offset:128
	v_bfe_u32 v6, v55, 16, 1
	v_add3_u32 v42, v55, v6, s28
	v_lshl_add_u64 v[6:7], v[30:31], 1, s[4:5]
	global_store_short_d16_hi v[6:7], v42, off offset:256
	v_bfe_u32 v42, v56, 16, 1
	v_add3_u32 v42, v56, v42, s28
	global_store_short_d16_hi v[6:7], v42, off offset:512
	v_bfe_u32 v42, v57, 16, 1
	v_add3_u32 v42, v57, v42, s28
	global_store_short_d16_hi v[6:7], v42, off offset:768
	v_bfe_u32 v6, v58, 16, 1
	v_add3_u32 v6, v58, v6, s28
	global_store_short_d16_hi v[4:5], v6, off offset:160
	v_bfe_u32 v6, v59, 16, 1
	v_add3_u32 v42, v59, v6, s28
	v_lshl_add_u64 v[6:7], v[32:33], 1, s[4:5]
	global_store_short_d16_hi v[6:7], v42, off offset:256
	v_bfe_u32 v42, v60, 16, 1
	v_add3_u32 v42, v60, v42, s28
	global_store_short_d16_hi v[6:7], v42, off offset:512
	v_bfe_u32 v42, v61, 16, 1
	v_add3_u32 v42, v61, v42, s28
	global_store_short_d16_hi v[6:7], v42, off offset:768
	v_bfe_u32 v6, v62, 16, 1
	v_add3_u32 v6, v62, v6, s28
	global_store_short_d16_hi v[4:5], v6, off offset:192
	v_bfe_u32 v6, v63, 16, 1
	v_add3_u32 v42, v63, v6, s28
	v_lshl_add_u64 v[6:7], v[34:35], 1, s[4:5]
	global_store_short_d16_hi v[6:7], v42, off offset:256
	v_bfe_u32 v42, v64, 16, 1
	v_add3_u32 v42, v64, v42, s28
	global_store_short_d16_hi v[6:7], v42, off offset:512
	v_bfe_u32 v42, v65, 16, 1
	v_add3_u32 v42, v65, v42, s28
	global_store_short_d16_hi v[6:7], v42, off offset:768
	v_bfe_u32 v6, v0, 16, 1
	v_add3_u32 v0, v0, v6, s28
	global_store_short_d16_hi v[4:5], v0, off offset:224
	v_bfe_u32 v0, v1, 16, 1
	v_add3_u32 v4, v1, v0, s28
	v_lshl_add_u64 v[0:1], v[36:37], 1, s[4:5]
	global_store_short_d16_hi v[0:1], v4, off offset:256
	v_bfe_u32 v4, v2, 16, 1
	v_add3_u32 v2, v2, v4, s28
	global_store_short_d16_hi v[0:1], v2, off offset:512
	v_bfe_u32 v2, v3, 16, 1
	v_add3_u32 v2, v3, v2, s28
	global_store_short_d16_hi v[0:1], v2, off offset:768
	s_and_saveexec_b64 s[4:5], s[44:45]
	s_cbranch_execz .LBB0_767
	s_add_i32 s2, s61, 0x9000
	v_mov_b32_e32 v0, 0
	s_mov_b32 s3, 0
